# sgemm fragment loads coalesced (lane->row lane>>2, 16B chunk lane&3) with in-register ds_bpermute to the MFMA layout; TCP tag-lookup bound removed
# speedup vs baseline: 1.0893x; 1.0256x over previous
.LBB0_475:
	v_lshrrev_b32_e32 v250, 2, v237
	v_and_b32_e32 v251, 15, v237
	v_sub_u32_e32 v250, v250, v251
	v_lshlrev_b32_e32 v250, 11, v250
	v_and_b32_e32 v251, 3, v237
	v_lshrrev_b32_e32 v248, 4, v237
	v_sub_u32_e32 v251, v251, v248
	v_lshl_add_u32 v250, v251, 4, v250
	v_ashrrev_i32_e32 v251, 31, v250
	v_and_b32_e32 v248, 15, v237
	v_lshlrev_b32_e32 v248, 4, v248
	v_lshrrev_b32_e32 v249, 4, v237
	v_lshl_or_b32 v248, v249, 2, v248
	v_lshl_add_u64 v[76:77], v[62:63], 0, s[28:29]
	v_lshl_add_u64 v[76:77], v[76:77], 0, v[250:251]
	v_lshl_add_u64 v[78:79], v[64:65], 0, s[28:29]
	v_lshl_add_u64 v[78:79], v[78:79], 0, v[250:251]
	v_add_co_u32_e32 v80, vcc, s89, v78
	s_nop 1
	v_addc_co_u32_e32 v81, vcc, 0, v79, vcc
	v_add_co_u32_e32 v82, vcc, s96, v78
	s_nop 1
	v_addc_co_u32_e32 v83, vcc, 0, v79, vcc
	v_add_co_u32_e32 v84, vcc, s71, v78
	s_nop 1
	v_addc_co_u32_e32 v85, vcc, 0, v79, vcc
	v_add_co_u32_e32 v86, vcc, s86, v78
	s_nop 1
	v_addc_co_u32_e32 v87, vcc, 0, v79, vcc
	v_add_co_u32_e32 v88, vcc, s88, v78
	s_nop 1
	v_addc_co_u32_e32 v89, vcc, 0, v79, vcc
	v_add_co_u32_e32 v90, vcc, s61, v78
	s_nop 1
	v_addc_co_u32_e32 v91, vcc, 0, v79, vcc
	v_add_co_u32_e32 v92, vcc, s65, v78
	s_nop 1
	v_addc_co_u32_e32 v93, vcc, 0, v79, vcc
	v_add_co_u32_e32 v78, vcc, s64, v78
	s_nop 1
	v_addc_co_u32_e32 v79, vcc, 0, v79, vcc
	global_load_dwordx4 v[118:121], v[76:77], off
	global_load_dwordx4 v[122:125], v[76:77], off offset:64
	global_load_dwordx4 v[126:129], v[76:77], off offset:128
	global_load_dwordx4 v[130:133], v[76:77], off offset:192
	global_load_dwordx4 v[134:137], v[80:81], off
	global_load_dwordx4 v[138:141], v[80:81], off offset:64
	global_load_dwordx4 v[142:145], v[82:83], off
	global_load_dwordx4 v[146:149], v[82:83], off offset:64
	global_load_dwordx4 v[150:153], v[84:85], off
	global_load_dwordx4 v[154:157], v[84:85], off offset:64
	global_load_dwordx4 v[158:161], v[86:87], off
	global_load_dwordx4 v[162:165], v[86:87], off offset:64
	global_load_dwordx4 v[166:169], v[88:89], off
	global_load_dwordx4 v[182:185], v[88:89], off offset:64
	global_load_dwordx4 v[186:189], v[90:91], off
	global_load_dwordx4 v[190:193], v[90:91], off offset:64
	global_load_dwordx4 v[194:197], v[92:93], off
	global_load_dwordx4 v[202:205], v[92:93], off offset:64
	global_load_dwordx4 v[206:209], v[78:79], off
	global_load_dwordx4 v[210:213], v[78:79], off offset:64
	global_load_dwordx4 v[214:217], v[80:81], off offset:128
	global_load_dwordx4 v[220:223], v[80:81], off offset:192
	global_load_dwordx4 v[224:227], v[82:83], off offset:128
	global_load_dwordx4 v[228:231], v[82:83], off offset:192
	global_load_dwordx4 v[232:235], v[84:85], off offset:128
	global_load_dwordx4 v[244:247], v[84:85], off offset:192
	s_waitcnt vmcnt(22)
	ds_bpermute_b32 v118, v248, v118
	ds_bpermute_b32 v119, v248, v119
	ds_bpermute_b32 v120, v248, v120
	ds_bpermute_b32 v121, v248, v121
	ds_bpermute_b32 v122, v248, v122
	ds_bpermute_b32 v123, v248, v123
	ds_bpermute_b32 v124, v248, v124
	ds_bpermute_b32 v125, v248, v125
	s_waitcnt lgkmcnt(7)
	ds_bpermute_b32 v126, v248, v126
	ds_bpermute_b32 v127, v248, v127
	ds_bpermute_b32 v128, v248, v128
	ds_bpermute_b32 v129, v248, v129
	ds_bpermute_b32 v130, v248, v130
	ds_bpermute_b32 v131, v248, v131
	ds_bpermute_b32 v132, v248, v132
	ds_bpermute_b32 v133, v248, v133
	s_waitcnt vmcnt(20) lgkmcnt(7)
	ds_bpermute_b32 v134, v248, v134
	ds_bpermute_b32 v135, v248, v135
	ds_bpermute_b32 v136, v248, v136
	ds_bpermute_b32 v137, v248, v137
	ds_bpermute_b32 v138, v248, v138
	ds_bpermute_b32 v139, v248, v139
	ds_bpermute_b32 v140, v248, v140
	ds_bpermute_b32 v141, v248, v141
	s_waitcnt vmcnt(18) lgkmcnt(7)
	ds_bpermute_b32 v142, v248, v142
	ds_bpermute_b32 v143, v248, v143
	ds_bpermute_b32 v144, v248, v144
	ds_bpermute_b32 v145, v248, v145
	ds_bpermute_b32 v146, v248, v146
	ds_bpermute_b32 v147, v248, v147
	ds_bpermute_b32 v148, v248, v148
	ds_bpermute_b32 v149, v248, v149
	s_waitcnt lgkmcnt(8)
	v_mfma_f32_16x16x32_bf16 v[36:39], v[118:121], v[134:137], v[36:39]
	v_mfma_f32_16x16x32_bf16 v[36:39], v[122:125], v[138:141], v[36:39]
	global_load_dwordx4 v[134:137], v[86:87], off offset:128
	global_load_dwordx4 v[138:141], v[86:87], off offset:192
	s_waitcnt vmcnt(18) lgkmcnt(7)
	ds_bpermute_b32 v150, v248, v150
	ds_bpermute_b32 v151, v248, v151
	ds_bpermute_b32 v152, v248, v152
	ds_bpermute_b32 v153, v248, v153
	ds_bpermute_b32 v154, v248, v154
	ds_bpermute_b32 v155, v248, v155
	ds_bpermute_b32 v156, v248, v156
	ds_bpermute_b32 v157, v248, v157
	s_waitcnt lgkmcnt(8)
	v_mfma_f32_16x16x32_bf16 v[32:35], v[118:121], v[142:145], v[32:35]
	v_mfma_f32_16x16x32_bf16 v[32:35], v[122:125], v[146:149], v[32:35]
	global_load_dwordx4 v[142:145], v[88:89], off offset:128
	global_load_dwordx4 v[146:149], v[88:89], off offset:192
	s_waitcnt vmcnt(18) lgkmcnt(7)
	ds_bpermute_b32 v158, v248, v158
	ds_bpermute_b32 v159, v248, v159
	ds_bpermute_b32 v160, v248, v160
	ds_bpermute_b32 v161, v248, v161
	ds_bpermute_b32 v162, v248, v162
	ds_bpermute_b32 v163, v248, v163
	ds_bpermute_b32 v164, v248, v164
	ds_bpermute_b32 v165, v248, v165
	s_waitcnt lgkmcnt(8)
	v_mfma_f32_16x16x32_bf16 v[28:31], v[118:121], v[150:153], v[28:31]
	v_mfma_f32_16x16x32_bf16 v[28:31], v[122:125], v[154:157], v[28:31]
	global_load_dwordx4 v[150:153], v[90:91], off offset:128
	global_load_dwordx4 v[154:157], v[90:91], off offset:192
	s_waitcnt vmcnt(18) lgkmcnt(7)
	ds_bpermute_b32 v166, v248, v166
	ds_bpermute_b32 v167, v248, v167
	ds_bpermute_b32 v168, v248, v168
	ds_bpermute_b32 v169, v248, v169
	ds_bpermute_b32 v182, v248, v182
	ds_bpermute_b32 v183, v248, v183
	ds_bpermute_b32 v184, v248, v184
	ds_bpermute_b32 v185, v248, v185
	s_waitcnt lgkmcnt(8)
	v_mfma_f32_16x16x32_bf16 v[24:27], v[118:121], v[158:161], v[24:27]
	v_mfma_f32_16x16x32_bf16 v[24:27], v[122:125], v[162:165], v[24:27]
	global_load_dwordx4 v[158:161], v[92:93], off offset:128
	global_load_dwordx4 v[162:165], v[92:93], off offset:192
	s_waitcnt vmcnt(18) lgkmcnt(7)
	ds_bpermute_b32 v186, v248, v186
	ds_bpermute_b32 v187, v248, v187
	ds_bpermute_b32 v188, v248, v188
	ds_bpermute_b32 v189, v248, v189
	ds_bpermute_b32 v190, v248, v190
	ds_bpermute_b32 v191, v248, v191
	ds_bpermute_b32 v192, v248, v192
	ds_bpermute_b32 v193, v248, v193
	s_waitcnt lgkmcnt(8)
	v_mfma_f32_16x16x32_bf16 v[20:23], v[118:121], v[166:169], v[20:23]
	v_mfma_f32_16x16x32_bf16 v[20:23], v[122:125], v[182:185], v[20:23]
	global_load_dwordx4 v[166:169], v[78:79], off offset:128
	global_load_dwordx4 v[182:185], v[78:79], off offset:192
	s_waitcnt vmcnt(18) lgkmcnt(7)
	ds_bpermute_b32 v194, v248, v194
	ds_bpermute_b32 v195, v248, v195
	ds_bpermute_b32 v196, v248, v196
	ds_bpermute_b32 v197, v248, v197
	ds_bpermute_b32 v202, v248, v202
	ds_bpermute_b32 v203, v248, v203
	ds_bpermute_b32 v204, v248, v204
	ds_bpermute_b32 v205, v248, v205
	s_waitcnt lgkmcnt(8)
	v_mfma_f32_16x16x32_bf16 v[16:19], v[118:121], v[186:189], v[16:19]
	v_mfma_f32_16x16x32_bf16 v[16:19], v[122:125], v[190:193], v[16:19]
	s_waitcnt vmcnt(16) lgkmcnt(7)
	ds_bpermute_b32 v206, v248, v206
	ds_bpermute_b32 v207, v248, v207
	ds_bpermute_b32 v208, v248, v208
	ds_bpermute_b32 v209, v248, v209
	ds_bpermute_b32 v210, v248, v210
	ds_bpermute_b32 v211, v248, v211
	ds_bpermute_b32 v212, v248, v212
	ds_bpermute_b32 v213, v248, v213
	s_waitcnt lgkmcnt(8)
	v_mfma_f32_16x16x32_bf16 v[12:15], v[118:121], v[194:197], v[12:15]
	v_mfma_f32_16x16x32_bf16 v[12:15], v[122:125], v[202:205], v[12:15]
	s_waitcnt vmcnt(14) lgkmcnt(7)
	ds_bpermute_b32 v214, v248, v214
	ds_bpermute_b32 v215, v248, v215
	ds_bpermute_b32 v216, v248, v216
	ds_bpermute_b32 v217, v248, v217
	ds_bpermute_b32 v220, v248, v220
	ds_bpermute_b32 v221, v248, v221
	ds_bpermute_b32 v222, v248, v222
	ds_bpermute_b32 v223, v248, v223
	s_waitcnt lgkmcnt(8)
	v_mfma_f32_16x16x32_bf16 v[8:11], v[118:121], v[206:209], v[8:11]
	v_mfma_f32_16x16x32_bf16 v[8:11], v[122:125], v[210:213], v[8:11]
	s_waitcnt vmcnt(12) lgkmcnt(7)
	ds_bpermute_b32 v224, v248, v224
	ds_bpermute_b32 v225, v248, v225
	ds_bpermute_b32 v226, v248, v226
	ds_bpermute_b32 v227, v248, v227
	ds_bpermute_b32 v228, v248, v228
	ds_bpermute_b32 v229, v248, v229
	ds_bpermute_b32 v230, v248, v230
	ds_bpermute_b32 v231, v248, v231
	s_waitcnt lgkmcnt(8)
	v_mfma_f32_16x16x32_bf16 v[36:39], v[126:129], v[214:217], v[36:39]
	v_mfma_f32_16x16x32_bf16 v[36:39], v[130:133], v[220:223], v[36:39]
	s_waitcnt vmcnt(10) lgkmcnt(7)
	ds_bpermute_b32 v232, v248, v232
	ds_bpermute_b32 v233, v248, v233
	ds_bpermute_b32 v234, v248, v234
	ds_bpermute_b32 v235, v248, v235
	ds_bpermute_b32 v244, v248, v244
	ds_bpermute_b32 v245, v248, v245
	ds_bpermute_b32 v246, v248, v246
	ds_bpermute_b32 v247, v248, v247
	s_waitcnt lgkmcnt(8)
	v_mfma_f32_16x16x32_bf16 v[32:35], v[126:129], v[224:227], v[32:35]
	v_mfma_f32_16x16x32_bf16 v[32:35], v[130:133], v[228:231], v[32:35]
	s_waitcnt vmcnt(8) lgkmcnt(7)
	ds_bpermute_b32 v134, v248, v134
	ds_bpermute_b32 v135, v248, v135
	ds_bpermute_b32 v136, v248, v136
	ds_bpermute_b32 v137, v248, v137
	ds_bpermute_b32 v138, v248, v138
	ds_bpermute_b32 v139, v248, v139
	ds_bpermute_b32 v140, v248, v140
	ds_bpermute_b32 v141, v248, v141
	s_waitcnt lgkmcnt(8)
	v_mfma_f32_16x16x32_bf16 v[28:31], v[126:129], v[232:235], v[28:31]
	v_mfma_f32_16x16x32_bf16 v[28:31], v[130:133], v[244:247], v[28:31]
	s_waitcnt vmcnt(6) lgkmcnt(7)
	ds_bpermute_b32 v142, v248, v142
	ds_bpermute_b32 v143, v248, v143
	ds_bpermute_b32 v144, v248, v144
	ds_bpermute_b32 v145, v248, v145
	ds_bpermute_b32 v146, v248, v146
	ds_bpermute_b32 v147, v248, v147
	ds_bpermute_b32 v148, v248, v148
	ds_bpermute_b32 v149, v248, v149
	s_waitcnt lgkmcnt(8)
	v_mfma_f32_16x16x32_bf16 v[24:27], v[126:129], v[134:137], v[24:27]
	v_mfma_f32_16x16x32_bf16 v[24:27], v[130:133], v[138:141], v[24:27]
	s_waitcnt vmcnt(4) lgkmcnt(7)
	ds_bpermute_b32 v150, v248, v150
	ds_bpermute_b32 v151, v248, v151
	ds_bpermute_b32 v152, v248, v152
	ds_bpermute_b32 v153, v248, v153
	ds_bpermute_b32 v154, v248, v154
	ds_bpermute_b32 v155, v248, v155
	ds_bpermute_b32 v156, v248, v156
	ds_bpermute_b32 v157, v248, v157
	s_waitcnt lgkmcnt(8)
	v_mfma_f32_16x16x32_bf16 v[20:23], v[126:129], v[142:145], v[20:23]
	v_mfma_f32_16x16x32_bf16 v[20:23], v[130:133], v[146:149], v[20:23]
	s_waitcnt vmcnt(2) lgkmcnt(7)
	ds_bpermute_b32 v158, v248, v158
	ds_bpermute_b32 v159, v248, v159
	ds_bpermute_b32 v160, v248, v160
	ds_bpermute_b32 v161, v248, v161
	ds_bpermute_b32 v162, v248, v162
	ds_bpermute_b32 v163, v248, v163
	ds_bpermute_b32 v164, v248, v164
	ds_bpermute_b32 v165, v248, v165
	s_waitcnt lgkmcnt(8)
	v_mfma_f32_16x16x32_bf16 v[16:19], v[126:129], v[150:153], v[16:19]
	v_mfma_f32_16x16x32_bf16 v[16:19], v[130:133], v[154:157], v[16:19]
	s_waitcnt vmcnt(0) lgkmcnt(7)
	ds_bpermute_b32 v166, v248, v166
	ds_bpermute_b32 v167, v248, v167
	ds_bpermute_b32 v168, v248, v168
	ds_bpermute_b32 v169, v248, v169
	ds_bpermute_b32 v182, v248, v182
	ds_bpermute_b32 v183, v248, v183
	ds_bpermute_b32 v184, v248, v184
	ds_bpermute_b32 v185, v248, v185
	s_waitcnt lgkmcnt(8)
	v_mfma_f32_16x16x32_bf16 v[12:15], v[126:129], v[158:161], v[12:15]
	v_mfma_f32_16x16x32_bf16 v[12:15], v[130:133], v[162:165], v[12:15]
	s_waitcnt lgkmcnt(0)
	v_mfma_f32_16x16x32_bf16 v[8:11], v[126:129], v[166:169], v[8:11]
	v_mfma_f32_16x16x32_bf16 v[8:11], v[130:133], v[182:185], v[8:11]
	s_nop 4
	v_add_u32_e32 v55, s20, v61
	ds_write_b128 v55, v[36:39]
	ds_write_b128 v55, v[32:35] offset:1024
	ds_write_b128 v55, v[28:31] offset:2048
	ds_write_b128 v55, v[24:27] offset:3072
	ds_write_b128 v55, v[20:23] offset:4096
	ds_write_b128 v55, v[16:19] offset:5120
	ds_write_b128 v55, v[12:15] offset:6144
	ds_write_b128 v55, v[8:11] offset:7168
	v_add_u32_e32 v24, s21, v61
	s_waitcnt lgkmcnt(0)
	s_barrier
	ds_read_b128 v[8:11], v24
	ds_read_b128 v[12:15], v24 offset:8192
	ds_read_b128 v[16:19], v24 offset:16384
	v_xor_b32_e32 v7, 0x80000000, v7
	v_xor_b32_e32 v6, 0x80000000, v6
	s_waitcnt lgkmcnt(2)
	v_pk_add_f32 v[10:11], v[10:11], 0 op_sel_hi:[1,0]
	v_pk_add_f32 v[20:21], v[8:9], 0 op_sel_hi:[1,0]
	s_waitcnt lgkmcnt(1)
	v_pk_add_f32 v[14:15], v[10:11], v[14:15]
	ds_read_b128 v[8:11], v24 offset:24576
	v_pk_add_f32 v[20:21], v[20:21], v[12:13]
	s_waitcnt lgkmcnt(1)
	v_pk_add_f32 v[18:19], v[14:15], v[18:19]
	ds_read_b128 v[12:15], v24 offset:32768
	v_pk_add_f32 v[16:17], v[20:21], v[16:17]
	s_waitcnt lgkmcnt(1)
	v_pk_add_f32 v[18:19], v[18:19], v[10:11]
	v_pk_add_f32 v[20:21], v[16:17], v[8:9]
	ds_read_b128 v[8:11], v24 offset:40960
	s_waitcnt lgkmcnt(1)
	v_pk_add_f32 v[22:23], v[18:19], v[14:15]
	ds_read_b128 v[14:17], v24 offset:49152
	v_pk_add_f32 v[12:13], v[20:21], v[12:13]
	ds_read_b128 v[18:21], v24 offset:57344
	s_waitcnt lgkmcnt(2)
	v_pk_add_f32 v[10:11], v[22:23], v[10:11]
	v_pk_add_f32 v[8:9], v[12:13], v[8:9]
	s_waitcnt lgkmcnt(1)
	v_pk_add_f32 v[10:11], v[10:11], v[16:17]
	v_pk_add_f32 v[8:9], v[8:9], v[14:15]
	s_waitcnt lgkmcnt(0)
	v_pk_add_f32 v[10:11], v[10:11], v[20:21]
	v_pk_add_f32 v[8:9], v[8:9], v[18:19]
	v_pk_fma_f32 v[6:7], v[6:7], v[58:59], v[10:11] op_sel_hi:[1,0,1]
	v_pk_fma_f32 v[4:5], v[4:5], v[58:59], v[8:9] op_sel_hi:[1,0,1] neg_lo:[1,0,0] neg_hi:[1,0,0]
	v_pk_fma_f32 v[2:3], v[60:61], v[6:7], v[2:3] op_sel_hi:[0,1,1]
	v_pk_fma_f32 v[0:1], v[60:61], v[4:5], v[0:1] op_sel_hi:[0,1,1]
	v_cndmask_b32_e64 v3, v3, v11, s[22:23]
	v_cndmask_b32_e64 v2, v2, v10, s[22:23]
	v_cndmask_b32_e64 v1, v1, v9, s[22:23]
	v_cndmask_b32_e64 v0, v0, v8, s[22:23]
	v_cmp_lt_i32_e32 vcc, s19, v56
	s_and_saveexec_b64 s[10:11], vcc
	s_xor_b64 s[10:11], exec, s[10:11]
	s_cbranch_execz .LBB0_485
	s_cmpk_gt_u32 s4, 0x2ff
	s_mov_b64 s[12:13], -1
	s_cbranch_scc0 .LBB0_479
	v_lshl_add_u64 v[4:5], v[56:57], 1, v[42:43]
	v_add_co_u32_e32 v4, vcc, 0x82af000, v4
	v_cvt_pk_bf16_f32 v6, v0, v1
	v_cvt_pk_bf16_f32 v7, v2, v3
	s_mov_b64 s[12:13], 0
	s_nop 0
	v_addc_co_u32_e32 v5, vcc, 0, v5, vcc
	global_store_dwordx2 v[4:5], v[6:7], off offset:2560

.LBB0_1096:
	v_lshrrev_b32_e32 v250, 2, v237
	v_and_b32_e32 v251, 15, v237
	v_sub_u32_e32 v250, v250, v251
	v_lshlrev_b32_e32 v250, 11, v250
	v_and_b32_e32 v251, 3, v237
	v_lshrrev_b32_e32 v248, 4, v237
	v_sub_u32_e32 v251, v251, v248
	v_lshl_add_u32 v250, v251, 4, v250
	v_ashrrev_i32_e32 v251, 31, v250
	v_and_b32_e32 v248, 15, v237
	v_lshlrev_b32_e32 v248, 4, v248
	v_lshrrev_b32_e32 v249, 4, v237
	v_lshl_or_b32 v248, v249, 2, v248
	v_lshl_add_u64 v[66:67], v[60:61], 0, s[42:43]
	v_lshl_add_u64 v[66:67], v[66:67], 0, v[250:251]
	s_mov_b32 s11, 0x600000
	v_add_co_u32_e32 v74, vcc, s11, v66
	v_lshl_add_u64 v[76:77], v[62:63], 0, s[42:43]
	v_lshl_add_u64 v[76:77], v[76:77], 0, v[250:251]
	s_nop 1
	v_addc_co_u32_e32 v75, vcc, 0, v67, vcc
	s_lshl_b32 s10, s101, 16
	s_mov_b32 s11, 0
	v_lshl_add_u64 v[76:77], v[76:77], 0, s[10:11]
	v_add_co_u32_e32 v78, vcc, s52, v76
	s_mov_b32 s11, 0x6a48000
	s_nop 1
	v_addc_co_u32_e32 v79, vcc, 0, v77, vcc
	v_add_co_u32_e32 v80, vcc, s11, v76
	s_nop 1
	v_addc_co_u32_e32 v81, vcc, 0, v77, vcc
	global_load_dwordx4 v[118:121], v[74:75], off
	global_load_dwordx4 v[122:125], v[74:75], off offset:64
	global_load_dwordx4 v[126:129], v[78:79], off
	global_load_dwordx4 v[130:133], v[78:79], off offset:64
	global_load_dwordx4 v[134:137], v[80:81], off
	global_load_dwordx4 v[138:141], v[80:81], off offset:64
	global_load_dwordx4 v[142:145], v[74:75], off offset:128
	global_load_dwordx4 v[146:149], v[74:75], off offset:192
	global_load_dwordx4 v[150:153], v[78:79], off offset:128
	global_load_dwordx4 v[154:157], v[78:79], off offset:192
	global_load_dwordx4 v[158:161], v[80:81], off offset:128
	global_load_dwordx4 v[162:165], v[80:81], off offset:192
	s_waitcnt vmcnt(10)
	ds_bpermute_b32 v118, v248, v118
	ds_bpermute_b32 v119, v248, v119
	ds_bpermute_b32 v120, v248, v120
	ds_bpermute_b32 v121, v248, v121
	ds_bpermute_b32 v122, v248, v122
	ds_bpermute_b32 v123, v248, v123
	ds_bpermute_b32 v124, v248, v124
	ds_bpermute_b32 v125, v248, v125
	s_waitcnt vmcnt(8) lgkmcnt(7)
	ds_bpermute_b32 v126, v248, v126
	ds_bpermute_b32 v127, v248, v127
	ds_bpermute_b32 v128, v248, v128
	ds_bpermute_b32 v129, v248, v129
	ds_bpermute_b32 v130, v248, v130
	ds_bpermute_b32 v131, v248, v131
	ds_bpermute_b32 v132, v248, v132
	ds_bpermute_b32 v133, v248, v133
	s_waitcnt lgkmcnt(8)
	s_waitcnt vmcnt(6) lgkmcnt(7)
	ds_bpermute_b32 v134, v248, v134
	ds_bpermute_b32 v135, v248, v135
	ds_bpermute_b32 v136, v248, v136
	ds_bpermute_b32 v137, v248, v137
	ds_bpermute_b32 v138, v248, v138
	ds_bpermute_b32 v139, v248, v139
	ds_bpermute_b32 v140, v248, v140
	ds_bpermute_b32 v141, v248, v141
	s_waitcnt lgkmcnt(8)
	s_waitcnt vmcnt(4) lgkmcnt(7)
	ds_bpermute_b32 v142, v248, v142
	ds_bpermute_b32 v143, v248, v143
	ds_bpermute_b32 v144, v248, v144
	ds_bpermute_b32 v145, v248, v145
	ds_bpermute_b32 v146, v248, v146
	ds_bpermute_b32 v147, v248, v147
	ds_bpermute_b32 v148, v248, v148
	ds_bpermute_b32 v149, v248, v149
	s_waitcnt lgkmcnt(8)
	v_mfma_f32_16x16x32_bf16 v[36:39], v[118:121], v[126:129], v[36:39]
	v_mfma_f32_16x16x32_bf16 v[32:35], v[118:121], v[134:137], v[32:35]
	v_mfma_f32_16x16x32_bf16 v[36:39], v[122:125], v[130:133], v[36:39]
	v_mfma_f32_16x16x32_bf16 v[32:35], v[122:125], v[138:141], v[32:35]
	s_waitcnt vmcnt(2) lgkmcnt(7)
	ds_bpermute_b32 v150, v248, v150
	ds_bpermute_b32 v151, v248, v151
	ds_bpermute_b32 v152, v248, v152
	ds_bpermute_b32 v153, v248, v153
	ds_bpermute_b32 v154, v248, v154
	ds_bpermute_b32 v155, v248, v155
	ds_bpermute_b32 v156, v248, v156
	ds_bpermute_b32 v157, v248, v157
	s_waitcnt lgkmcnt(8)
	s_waitcnt vmcnt(0) lgkmcnt(7)
	ds_bpermute_b32 v158, v248, v158
	ds_bpermute_b32 v159, v248, v159
	ds_bpermute_b32 v160, v248, v160
	ds_bpermute_b32 v161, v248, v161
	ds_bpermute_b32 v162, v248, v162
	ds_bpermute_b32 v163, v248, v163
	ds_bpermute_b32 v164, v248, v164
	ds_bpermute_b32 v165, v248, v165
	s_waitcnt lgkmcnt(8)
	s_waitcnt lgkmcnt(0)
	v_mfma_f32_16x16x32_bf16 v[36:39], v[142:145], v[150:153], v[36:39]
	v_mfma_f32_16x16x32_bf16 v[32:35], v[142:145], v[158:161], v[32:35]
	v_mfma_f32_16x16x32_bf16 v[36:39], v[146:149], v[154:157], v[36:39]
	v_mfma_f32_16x16x32_bf16 v[32:35], v[146:149], v[162:165], v[32:35]
	s_nop 4
	v_add_u32_e32 v49, s4, v55
	v_lshl_add_u32 v49, s101, 11, v49
	ds_write_b128 v49, v[36:39]
	ds_write_b128 v49, v[32:35] offset:1024
	v_add_u32_e32 v24, s12, v55
	s_waitcnt lgkmcnt(0)
	s_barrier
	s_lshr_b32 s10, s12, 11
	s_cmp_lg_u32 s10, s101
	s_cbranch_scc1 .LBB0_1092
	ds_read_b128 v[8:11], v24
	ds_read_b128 v[12:15], v24 offset:8192
	ds_read_b128 v[16:19], v24 offset:16384
	s_waitcnt lgkmcnt(2)
	v_pk_add_f32 v[10:11], v[10:11], 0 op_sel_hi:[1,0]
	v_pk_add_f32 v[20:21], v[8:9], 0 op_sel_hi:[1,0]
	s_waitcnt lgkmcnt(1)
	v_pk_add_f32 v[14:15], v[10:11], v[14:15]
	ds_read_b128 v[8:11], v24 offset:24576
	v_pk_add_f32 v[20:21], v[20:21], v[12:13]
	s_waitcnt lgkmcnt(1)
	v_pk_add_f32 v[18:19], v[14:15], v[18:19]
	ds_read_b128 v[12:15], v24 offset:32768
	v_pk_add_f32 v[16:17], v[20:21], v[16:17]
	s_waitcnt lgkmcnt(1)
	v_pk_add_f32 v[18:19], v[18:19], v[10:11]
	v_pk_add_f32 v[20:21], v[16:17], v[8:9]
	ds_read_b128 v[8:11], v24 offset:40960
	s_waitcnt lgkmcnt(1)
	v_pk_add_f32 v[22:23], v[18:19], v[14:15]
	ds_read_b128 v[14:17], v24 offset:49152
	v_pk_add_f32 v[12:13], v[20:21], v[12:13]
	ds_read_b128 v[18:21], v24 offset:57344
	s_waitcnt lgkmcnt(2)
	v_pk_add_f32 v[8:9], v[12:13], v[8:9]
	v_pk_add_f32 v[10:11], v[22:23], v[10:11]
	s_waitcnt lgkmcnt(1)
	v_pk_add_f32 v[8:9], v[8:9], v[14:15]
	v_pk_add_f32 v[10:11], v[10:11], v[16:17]
	s_waitcnt lgkmcnt(0)
	v_pk_add_f32 v[8:9], v[8:9], v[18:19]
	v_lshlrev_b32_e32 v18, 16, v59
	v_and_b32_e32 v19, 0xffff0000, v59
	v_lshlrev_b32_e32 v16, 16, v58
	v_and_b32_e32 v17, 0xffff0000, v58
	v_sub_f32_e32 v13, v19, v56
	v_sub_f32_e32 v12, v18, v56
	v_sub_f32_e32 v15, v17, v56
	v_sub_f32_e32 v14, v16, v56
	v_pk_mul_f32 v[12:13], v[54:55], v[12:13] op_sel_hi:[0,1]
	v_pk_mul_f32 v[14:15], v[54:55], v[14:15] op_sel_hi:[0,1]
	v_pk_fma_f32 v[2:3], v[2:3], v[12:13], v[6:7]
	v_pk_add_f32 v[10:11], v[10:11], v[20:21]
	v_pk_fma_f32 v[0:1], v[0:1], v[14:15], v[4:5]
	v_cndmask_b32_e64 v3, v3, v19, s[28:29]
	v_cndmask_b32_e64 v2, v2, v18, s[28:29]
	v_cndmask_b32_e64 v1, v1, v17, s[28:29]
	v_cndmask_b32_e64 v0, v0, v16, s[28:29]
	v_pk_fma_f32 v[4:5], v[2:3], s[70:71], v[10:11] op_sel_hi:[1,0,1]
	v_and_b32_e32 v2, 64, v237
	v_pk_fma_f32 v[6:7], v[0:1], s[70:71], v[8:9] op_sel_hi:[1,0,1]
	v_xor_b32_e32 v0, 16, v237
	v_add_u32_e32 v12, 64, v2
	v_cmp_lt_i32_e32 vcc, v0, v12
	v_mul_f32_e32 v1, v6, v6
	v_mul_f32_e32 v3, v7, v7
	v_cndmask_b32_e32 v0, v237, v0, vcc
	v_mul_f32_e32 v9, v4, v4
	v_mul_f32_e32 v11, v5, v5
	v_lshlrev_b32_e32 v13, 2, v0
	v_mov_b32_e32 v0, v6
	v_mov_b32_e32 v2, v7
	v_mov_b32_e32 v8, v4
	v_mov_b32_e32 v10, v5
	v_pk_add_f32 v[0:1], v[0:1], v[2:3]
	v_pk_add_f32 v[2:3], v[8:9], v[10:11]
	v_xor_b32_e32 v8, 32, v237
	v_pk_add_f32 v[0:1], v[0:1], v[2:3]
	ds_bpermute_b32 v2, v13, v0
	ds_bpermute_b32 v3, v13, v1
	v_cmp_lt_i32_e32 vcc, v8, v12
	v_cvt_pk_bf16_f32 v6, v6, v7
	v_cvt_pk_bf16_f32 v7, v4, v5
	global_store_dwordx2 v[52:53], v[6:7], off
	s_waitcnt lgkmcnt(0)
	v_pk_add_f32 v[0:1], v[0:1], v[2:3]
	v_cndmask_b32_e32 v8, v237, v8, vcc
	v_lshlrev_b32_e32 v8, 2, v8
	ds_bpermute_b32 v2, v8, v0
	ds_bpermute_b32 v3, v8, v1
	s_and_saveexec_b64 s[10:11], s[30:31]
	s_cbranch_execz .LBB0_1092
	s_lshl_b32 s16, s100, 1
	s_ashr_i32 s17, s16, 31
	v_lshl_add_u64 v[4:5], s[16:17], 2, v[44:45]
	s_waitcnt lgkmcnt(0)
	v_pk_add_f32 v[0:1], v[0:1], v[2:3]
	global_store_dwordx2 v[4:5], v[0:1], off
	s_branch .LBB0_1092

.LBB0_1271:
	v_lshrrev_b32_e32 v250, 2, v237
	v_and_b32_e32 v251, 15, v237
	v_sub_u32_e32 v250, v250, v251
	v_lshlrev_b32_e32 v250, 11, v250
	v_and_b32_e32 v251, 3, v237
	v_lshrrev_b32_e32 v248, 4, v237
	v_sub_u32_e32 v251, v251, v248
	v_lshl_add_u32 v250, v251, 4, v250
	v_ashrrev_i32_e32 v251, 31, v250
	v_and_b32_e32 v248, 15, v237
	v_lshlrev_b32_e32 v248, 4, v248
	v_lshrrev_b32_e32 v249, 4, v237
	v_lshl_or_b32 v248, v249, 2, v248
	v_lshl_add_u64 v[92:93], v[82:83], 0, s[28:29]
	v_lshl_add_u64 v[92:93], v[92:93], 0, v[250:251]
	s_mov_b32 s13, 0xa00000
	v_add_co_u32_e32 v100, vcc, s13, v92
	v_lshl_add_u64 v[102:103], v[86:87], 0, s[28:29]
	v_lshl_add_u64 v[102:103], v[102:103], 0, v[250:251]
	s_nop 1
	v_addc_co_u32_e32 v101, vcc, 0, v93, vcc
	v_add_co_u32_e32 v104, vcc, s89, v102
	s_nop 1
	v_addc_co_u32_e32 v105, vcc, 0, v103, vcc
	v_add_co_u32_e32 v106, vcc, s96, v102
	s_nop 1
	v_addc_co_u32_e32 v107, vcc, 0, v103, vcc
	v_add_co_u32_e32 v108, vcc, s71, v102
	s_nop 1
	v_addc_co_u32_e32 v109, vcc, 0, v103, vcc
	v_add_co_u32_e32 v110, vcc, s86, v102
	s_nop 1
	v_addc_co_u32_e32 v111, vcc, 0, v103, vcc
	v_add_co_u32_e32 v112, vcc, s88, v102
	s_nop 1
	v_addc_co_u32_e32 v113, vcc, 0, v103, vcc
	v_add_co_u32_e32 v114, vcc, s61, v102
	s_nop 1
	v_addc_co_u32_e32 v115, vcc, 0, v103, vcc
	v_add_co_u32_e32 v116, vcc, s65, v102
	s_nop 1
	v_addc_co_u32_e32 v117, vcc, 0, v103, vcc
	v_add_co_u32_e32 v102, vcc, s64, v102
	s_nop 1
	v_addc_co_u32_e32 v103, vcc, 0, v103, vcc
	global_load_dwordx4 v[118:121], v[100:101], off
	global_load_dwordx4 v[122:125], v[100:101], off offset:64
	global_load_dwordx4 v[126:129], v[100:101], off offset:128
	global_load_dwordx4 v[130:133], v[100:101], off offset:192
	global_load_dwordx4 v[134:137], v[104:105], off
	global_load_dwordx4 v[138:141], v[104:105], off offset:64
	global_load_dwordx4 v[142:145], v[106:107], off
	global_load_dwordx4 v[146:149], v[106:107], off offset:64
	global_load_dwordx4 v[150:153], v[108:109], off
	global_load_dwordx4 v[154:157], v[108:109], off offset:64
	global_load_dwordx4 v[158:161], v[110:111], off
	global_load_dwordx4 v[162:165], v[110:111], off offset:64
	global_load_dwordx4 v[166:169], v[112:113], off
	global_load_dwordx4 v[182:185], v[112:113], off offset:64
	global_load_dwordx4 v[186:189], v[114:115], off
	global_load_dwordx4 v[190:193], v[114:115], off offset:64
	global_load_dwordx4 v[194:197], v[116:117], off
	global_load_dwordx4 v[202:205], v[116:117], off offset:64
	global_load_dwordx4 v[206:209], v[102:103], off
	global_load_dwordx4 v[210:213], v[102:103], off offset:64
	global_load_dwordx4 v[214:217], v[104:105], off offset:128
	global_load_dwordx4 v[220:223], v[104:105], off offset:192
	global_load_dwordx4 v[224:227], v[106:107], off offset:128
	global_load_dwordx4 v[228:231], v[106:107], off offset:192
	global_load_dwordx4 v[232:235], v[108:109], off offset:128
	global_load_dwordx4 v[244:247], v[108:109], off offset:192
	s_waitcnt vmcnt(22)
	ds_bpermute_b32 v118, v248, v118
	ds_bpermute_b32 v119, v248, v119
	ds_bpermute_b32 v120, v248, v120
	ds_bpermute_b32 v121, v248, v121
	ds_bpermute_b32 v122, v248, v122
	ds_bpermute_b32 v123, v248, v123
	ds_bpermute_b32 v124, v248, v124
	ds_bpermute_b32 v125, v248, v125
	s_waitcnt lgkmcnt(7)
	ds_bpermute_b32 v126, v248, v126
	ds_bpermute_b32 v127, v248, v127
	ds_bpermute_b32 v128, v248, v128
	ds_bpermute_b32 v129, v248, v129
	ds_bpermute_b32 v130, v248, v130
	ds_bpermute_b32 v131, v248, v131
	ds_bpermute_b32 v132, v248, v132
	ds_bpermute_b32 v133, v248, v133
	s_waitcnt vmcnt(20) lgkmcnt(7)
	ds_bpermute_b32 v134, v248, v134
	ds_bpermute_b32 v135, v248, v135
	ds_bpermute_b32 v136, v248, v136
	ds_bpermute_b32 v137, v248, v137
	ds_bpermute_b32 v138, v248, v138
	ds_bpermute_b32 v139, v248, v139
	ds_bpermute_b32 v140, v248, v140
	ds_bpermute_b32 v141, v248, v141
	s_waitcnt vmcnt(18) lgkmcnt(7)
	ds_bpermute_b32 v142, v248, v142
	ds_bpermute_b32 v143, v248, v143
	ds_bpermute_b32 v144, v248, v144
	ds_bpermute_b32 v145, v248, v145
	ds_bpermute_b32 v146, v248, v146
	ds_bpermute_b32 v147, v248, v147
	ds_bpermute_b32 v148, v248, v148
	ds_bpermute_b32 v149, v248, v149
	s_waitcnt lgkmcnt(8)
	v_mfma_f32_16x16x32_bf16 v[64:67], v[118:121], v[134:137], v[64:67]
	v_mfma_f32_16x16x32_bf16 v[64:67], v[122:125], v[138:141], v[64:67]
	global_load_dwordx4 v[134:137], v[110:111], off offset:128
	global_load_dwordx4 v[138:141], v[110:111], off offset:192
	s_waitcnt vmcnt(18) lgkmcnt(7)
	ds_bpermute_b32 v150, v248, v150
	ds_bpermute_b32 v151, v248, v151
	ds_bpermute_b32 v152, v248, v152
	ds_bpermute_b32 v153, v248, v153
	ds_bpermute_b32 v154, v248, v154
	ds_bpermute_b32 v155, v248, v155
	ds_bpermute_b32 v156, v248, v156
	ds_bpermute_b32 v157, v248, v157
	s_waitcnt lgkmcnt(8)
	v_mfma_f32_16x16x32_bf16 v[60:63], v[118:121], v[142:145], v[60:63]
	v_mfma_f32_16x16x32_bf16 v[60:63], v[122:125], v[146:149], v[60:63]
	global_load_dwordx4 v[142:145], v[112:113], off offset:128
	global_load_dwordx4 v[146:149], v[112:113], off offset:192
	s_waitcnt vmcnt(18) lgkmcnt(7)
	ds_bpermute_b32 v158, v248, v158
	ds_bpermute_b32 v159, v248, v159
	ds_bpermute_b32 v160, v248, v160
	ds_bpermute_b32 v161, v248, v161
	ds_bpermute_b32 v162, v248, v162
	ds_bpermute_b32 v163, v248, v163
	ds_bpermute_b32 v164, v248, v164
	ds_bpermute_b32 v165, v248, v165
	s_waitcnt lgkmcnt(8)
	v_mfma_f32_16x16x32_bf16 v[56:59], v[118:121], v[150:153], v[56:59]
	v_mfma_f32_16x16x32_bf16 v[56:59], v[122:125], v[154:157], v[56:59]
	global_load_dwordx4 v[150:153], v[114:115], off offset:128
	global_load_dwordx4 v[154:157], v[114:115], off offset:192
	s_waitcnt vmcnt(18) lgkmcnt(7)
	ds_bpermute_b32 v166, v248, v166
	ds_bpermute_b32 v167, v248, v167
	ds_bpermute_b32 v168, v248, v168
	ds_bpermute_b32 v169, v248, v169
	ds_bpermute_b32 v182, v248, v182
	ds_bpermute_b32 v183, v248, v183
	ds_bpermute_b32 v184, v248, v184
	ds_bpermute_b32 v185, v248, v185
	s_waitcnt lgkmcnt(8)
	v_mfma_f32_16x16x32_bf16 v[52:55], v[118:121], v[158:161], v[52:55]
	v_mfma_f32_16x16x32_bf16 v[52:55], v[122:125], v[162:165], v[52:55]
	global_load_dwordx4 v[158:161], v[116:117], off offset:128
	global_load_dwordx4 v[162:165], v[116:117], off offset:192
	s_waitcnt vmcnt(18) lgkmcnt(7)
	ds_bpermute_b32 v186, v248, v186
	ds_bpermute_b32 v187, v248, v187
	ds_bpermute_b32 v188, v248, v188
	ds_bpermute_b32 v189, v248, v189
	ds_bpermute_b32 v190, v248, v190
	ds_bpermute_b32 v191, v248, v191
	ds_bpermute_b32 v192, v248, v192
	ds_bpermute_b32 v193, v248, v193
	s_waitcnt lgkmcnt(8)
	v_mfma_f32_16x16x32_bf16 v[48:51], v[118:121], v[166:169], v[48:51]
	v_mfma_f32_16x16x32_bf16 v[48:51], v[122:125], v[182:185], v[48:51]
	global_load_dwordx4 v[166:169], v[102:103], off offset:128
	global_load_dwordx4 v[182:185], v[102:103], off offset:192
	s_waitcnt vmcnt(18) lgkmcnt(7)
	ds_bpermute_b32 v194, v248, v194
	ds_bpermute_b32 v195, v248, v195
	ds_bpermute_b32 v196, v248, v196
	ds_bpermute_b32 v197, v248, v197
	ds_bpermute_b32 v202, v248, v202
	ds_bpermute_b32 v203, v248, v203
	ds_bpermute_b32 v204, v248, v204
	ds_bpermute_b32 v205, v248, v205
	s_waitcnt lgkmcnt(8)
	v_mfma_f32_16x16x32_bf16 v[44:47], v[118:121], v[186:189], v[44:47]
	v_mfma_f32_16x16x32_bf16 v[44:47], v[122:125], v[190:193], v[44:47]
	s_waitcnt vmcnt(16) lgkmcnt(7)
	ds_bpermute_b32 v206, v248, v206
	ds_bpermute_b32 v207, v248, v207
	ds_bpermute_b32 v208, v248, v208
	ds_bpermute_b32 v209, v248, v209
	ds_bpermute_b32 v210, v248, v210
	ds_bpermute_b32 v211, v248, v211
	ds_bpermute_b32 v212, v248, v212
	ds_bpermute_b32 v213, v248, v213
	s_waitcnt lgkmcnt(8)
	v_mfma_f32_16x16x32_bf16 v[68:71], v[118:121], v[194:197], v[68:71]
	v_mfma_f32_16x16x32_bf16 v[68:71], v[122:125], v[202:205], v[68:71]
	s_waitcnt vmcnt(14) lgkmcnt(7)
	ds_bpermute_b32 v214, v248, v214
	ds_bpermute_b32 v215, v248, v215
	ds_bpermute_b32 v216, v248, v216
	ds_bpermute_b32 v217, v248, v217
	ds_bpermute_b32 v220, v248, v220
	ds_bpermute_b32 v221, v248, v221
	ds_bpermute_b32 v222, v248, v222
	ds_bpermute_b32 v223, v248, v223
	s_waitcnt lgkmcnt(8)
	v_mfma_f32_16x16x32_bf16 v[28:31], v[118:121], v[206:209], v[28:31]
	v_mfma_f32_16x16x32_bf16 v[28:31], v[122:125], v[210:213], v[28:31]
	s_waitcnt vmcnt(12) lgkmcnt(7)
	ds_bpermute_b32 v224, v248, v224
	ds_bpermute_b32 v225, v248, v225
	ds_bpermute_b32 v226, v248, v226
	ds_bpermute_b32 v227, v248, v227
	ds_bpermute_b32 v228, v248, v228
	ds_bpermute_b32 v229, v248, v229
	ds_bpermute_b32 v230, v248, v230
	ds_bpermute_b32 v231, v248, v231
	s_waitcnt lgkmcnt(8)
	v_mfma_f32_16x16x32_bf16 v[64:67], v[126:129], v[214:217], v[64:67]
	v_mfma_f32_16x16x32_bf16 v[64:67], v[130:133], v[220:223], v[64:67]
	s_waitcnt vmcnt(10) lgkmcnt(7)
	ds_bpermute_b32 v232, v248, v232
	ds_bpermute_b32 v233, v248, v233
	ds_bpermute_b32 v234, v248, v234
	ds_bpermute_b32 v235, v248, v235
	ds_bpermute_b32 v244, v248, v244
	ds_bpermute_b32 v245, v248, v245
	ds_bpermute_b32 v246, v248, v246
	ds_bpermute_b32 v247, v248, v247
	s_waitcnt lgkmcnt(8)
	v_mfma_f32_16x16x32_bf16 v[60:63], v[126:129], v[224:227], v[60:63]
	v_mfma_f32_16x16x32_bf16 v[60:63], v[130:133], v[228:231], v[60:63]
	s_waitcnt vmcnt(8) lgkmcnt(7)
	ds_bpermute_b32 v134, v248, v134
	ds_bpermute_b32 v135, v248, v135
	ds_bpermute_b32 v136, v248, v136
	ds_bpermute_b32 v137, v248, v137
	ds_bpermute_b32 v138, v248, v138
	ds_bpermute_b32 v139, v248, v139
	ds_bpermute_b32 v140, v248, v140
	ds_bpermute_b32 v141, v248, v141
	s_waitcnt lgkmcnt(8)
	v_mfma_f32_16x16x32_bf16 v[56:59], v[126:129], v[232:235], v[56:59]
	v_mfma_f32_16x16x32_bf16 v[56:59], v[130:133], v[244:247], v[56:59]
	s_waitcnt vmcnt(6) lgkmcnt(7)
	ds_bpermute_b32 v142, v248, v142
	ds_bpermute_b32 v143, v248, v143
	ds_bpermute_b32 v144, v248, v144
	ds_bpermute_b32 v145, v248, v145
	ds_bpermute_b32 v146, v248, v146
	ds_bpermute_b32 v147, v248, v147
	ds_bpermute_b32 v148, v248, v148
	ds_bpermute_b32 v149, v248, v149
	s_waitcnt lgkmcnt(8)
	v_mfma_f32_16x16x32_bf16 v[52:55], v[126:129], v[134:137], v[52:55]
	v_mfma_f32_16x16x32_bf16 v[52:55], v[130:133], v[138:141], v[52:55]
	s_waitcnt vmcnt(4) lgkmcnt(7)
	ds_bpermute_b32 v150, v248, v150
	ds_bpermute_b32 v151, v248, v151
	ds_bpermute_b32 v152, v248, v152
	ds_bpermute_b32 v153, v248, v153
	ds_bpermute_b32 v154, v248, v154
	ds_bpermute_b32 v155, v248, v155
	ds_bpermute_b32 v156, v248, v156
	ds_bpermute_b32 v157, v248, v157
	s_waitcnt lgkmcnt(8)
	v_mfma_f32_16x16x32_bf16 v[48:51], v[126:129], v[142:145], v[48:51]
	v_mfma_f32_16x16x32_bf16 v[48:51], v[130:133], v[146:149], v[48:51]
	s_waitcnt vmcnt(2) lgkmcnt(7)
	ds_bpermute_b32 v158, v248, v158
	ds_bpermute_b32 v159, v248, v159
	ds_bpermute_b32 v160, v248, v160
	ds_bpermute_b32 v161, v248, v161
	ds_bpermute_b32 v162, v248, v162
	ds_bpermute_b32 v163, v248, v163
	ds_bpermute_b32 v164, v248, v164
	ds_bpermute_b32 v165, v248, v165
	s_waitcnt lgkmcnt(8)
	v_mfma_f32_16x16x32_bf16 v[44:47], v[126:129], v[150:153], v[44:47]
	v_mfma_f32_16x16x32_bf16 v[44:47], v[130:133], v[154:157], v[44:47]
	s_waitcnt vmcnt(0) lgkmcnt(7)
	ds_bpermute_b32 v166, v248, v166
	ds_bpermute_b32 v167, v248, v167
	ds_bpermute_b32 v168, v248, v168
	ds_bpermute_b32 v169, v248, v169
	ds_bpermute_b32 v182, v248, v182
	ds_bpermute_b32 v183, v248, v183
	ds_bpermute_b32 v184, v248, v184
	ds_bpermute_b32 v185, v248, v185
	s_waitcnt lgkmcnt(8)
	v_mfma_f32_16x16x32_bf16 v[68:71], v[126:129], v[158:161], v[68:71]
	v_mfma_f32_16x16x32_bf16 v[68:71], v[130:133], v[162:165], v[68:71]
	s_waitcnt lgkmcnt(0)
	v_mfma_f32_16x16x32_bf16 v[28:31], v[126:129], v[166:169], v[28:31]
	v_mfma_f32_16x16x32_bf16 v[28:31], v[130:133], v[182:185], v[28:31]
	s_nop 4
	v_add_f32_e32 v4, v13, v15
	v_add_f32_e32 v6, v9, v11
	v_add_f32_e32 v4, 0, v4
	v_add_f32_e32 v5, v5, v7
	v_add_f32_e32 v4, v4, v6
	v_add_f32_e32 v1, v1, v3
	v_add_f32_e32 v4, v4, v5
	v_add_f32_e32 v3, v41, v43
	v_add_f32_e32 v1, v4, v1
	v_add_f32_e32 v7, v25, v27
	v_add_f32_e32 v1, v1, v3
	v_add_f32_e32 v8, v21, v23
	v_add_f32_e32 v1, v1, v7
	v_add_f32_e32 v9, v17, v19
	v_add_f32_e32 v1, v1, v8
	v_add_f32_e32 v8, v1, v9
	v_add_u32_e32 v1, s4, v88
	v_add_u32_e32 v18, s10, v88
	ds_bpermute_b32 v9, v89, v8
	ds_write_b128 v1, v[64:67]
	ds_write_b128 v1, v[60:63] offset:1024
	ds_write_b128 v1, v[56:59] offset:2048
	ds_write_b128 v1, v[52:55] offset:3072
	ds_write_b128 v1, v[48:51] offset:4096
	ds_write_b128 v1, v[44:47] offset:5120
	ds_write_b128 v1, v[68:71] offset:6144
	ds_write_b128 v1, v[28:31] offset:7168
	s_waitcnt lgkmcnt(0)
	s_barrier
	ds_read_b128 v[4:7], v18
	v_add_f32_e32 v13, v0, v2
	ds_read_b128 v[0:3], v18 offset:8192
	v_add_f32_e32 v12, v8, v9
	ds_bpermute_b32 v15, v90, v13
	s_waitcnt lgkmcnt(2)
	v_pk_add_f32 v[10:11], v[6:7], 0 op_sel_hi:[1,0]
	ds_read_b128 v[6:9], v18 offset:16384
	v_pk_add_f32 v[16:17], v[4:5], 0 op_sel_hi:[1,0]
	s_waitcnt lgkmcnt(2)
	v_pk_add_f32 v[10:11], v[10:11], v[2:3]
	ds_read_b128 v[2:5], v18 offset:24576
	v_pk_add_f32 v[0:1], v[16:17], v[0:1]
	s_waitcnt lgkmcnt(1)
	v_pk_add_f32 v[16:17], v[10:11], v[8:9]
	ds_read_b128 v[8:11], v18 offset:32768
	v_pk_add_f32 v[0:1], v[0:1], v[6:7]
	s_waitcnt lgkmcnt(1)
	v_pk_add_f32 v[4:5], v[16:17], v[4:5]
	v_pk_add_f32 v[6:7], v[0:1], v[2:3]
	ds_read_b128 v[0:3], v18 offset:40960
	s_waitcnt lgkmcnt(1)
	v_pk_add_f32 v[10:11], v[4:5], v[10:11]
	v_pk_add_f32 v[8:9], v[6:7], v[8:9]
	ds_read_b128 v[4:7], v18 offset:49152
	ds_bpermute_b32 v14, v90, v12
	s_waitcnt lgkmcnt(2)
	v_pk_add_f32 v[10:11], v[10:11], v[2:3]
	v_pk_add_f32 v[8:9], v[8:9], v[0:1]
	ds_read_b128 v[0:3], v18 offset:57344
	s_waitcnt lgkmcnt(2)
	v_pk_add_f32 v[6:7], v[10:11], v[6:7]
	s_waitcnt lgkmcnt(1)
	v_pk_add_f32 v[10:11], v[12:13], v[14:15]
	v_pk_add_f32 v[4:5], v[8:9], v[4:5]
	v_pk_mul_f32 v[10:11], v[10:11], s[6:7] op_sel_hi:[1,0]
	s_waitcnt lgkmcnt(0)
	v_pk_add_f32 v[0:1], v[4:5], v[0:1]
	v_fma_f32 v12, -v11, v11, v10
	v_max_f32_e32 v12, 0, v12
	v_add_f32_e32 v12, 0x3727c5ac, v12
	v_mul_f32_e32 v13, 0x4b800000, v12
	v_cmp_gt_f32_e32 vcc, s14, v12
	v_pk_add_f32 v[2:3], v[6:7], v[2:3]
	v_pk_fma_f32 v[0:1], v[32:33], v[10:11], v[0:1] op_sel:[0,1,0] neg_lo:[1,0,0] neg_hi:[1,0,0]
	v_cndmask_b32_e32 v12, v12, v13, vcc
	v_rsq_f32_e32 v12, v12
	v_xor_b32_e32 v7, 0x80000000, v35
	v_xor_b32_e32 v6, 0x80000000, v34
	v_pk_fma_f32 v[2:3], v[6:7], v[10:11], v[2:3] op_sel:[0,1,0]
	v_mul_f32_e32 v4, 0x45800000, v12
	v_cndmask_b32_e32 v4, v12, v4, vcc
	v_pk_fma_f32 v[0:1], v[0:1], v[4:5], v[36:37] op_sel_hi:[1,0,1]
	v_pk_fma_f32 v[2:3], v[2:3], v[4:5], v[38:39] op_sel_hi:[1,0,1]
	v_max_f32_e32 v0, 0, v0
	v_max_f32_e32 v1, 0, v1
	s_add_i32 s11, s11, s3
	v_max_f32_e32 v2, 0, v2
	v_max_f32_e32 v3, 0, v3
	v_pk_mul_f32 v[0:1], v[0:1], v[0:1]
	v_lshl_add_u64 v[4:5], v[84:85], 1, v[74:75]
	s_cmpk_lt_i32 s11, 0x100
	v_add_u32_e32 v78, s87, v78
	v_pk_mul_f32 v[2:3], v[2:3], v[2:3]
	v_cvt_pk_bf16_f32 v0, v0, v1
	s_nop 0
	v_cvt_pk_bf16_f32 v1, v2, v3
	global_store_dwordx2 v[4:5], v[0:1], off
	s_barrier
	s_cbranch_scc1 .LBB0_1270

.LBB0_1375:
	v_lshrrev_b32_e32 v250, 2, v237
	v_and_b32_e32 v251, 15, v237
	v_sub_u32_e32 v250, v250, v251
	v_lshlrev_b32_e32 v250, 13, v250
	v_and_b32_e32 v251, 3, v237
	v_lshrrev_b32_e32 v248, 4, v237
	v_sub_u32_e32 v251, v251, v248
	v_lshl_add_u32 v250, v251, 4, v250
	v_ashrrev_i32_e32 v251, 31, v250
	v_and_b32_e32 v248, 15, v237
	v_lshlrev_b32_e32 v248, 4, v248
	v_lshrrev_b32_e32 v249, 4, v237
	v_lshl_or_b32 v248, v249, 2, v248
	v_lshl_add_u64 v[68:69], v[52:53], 0, s[34:35]
	v_lshl_add_u64 v[68:69], v[68:69], 0, v[250:251]
	s_mov_b32 s11, 0x1a00000
	v_add_co_u32_e64 v76, s[22:23], s11, v68
	v_lshl_add_u64 v[78:79], v[62:63], 0, s[34:35]
	v_lshl_add_u64 v[78:79], v[78:79], 0, v[250:251]
	s_nop 1
	v_addc_co_u32_e64 v77, s[22:23], 0, v69, s[22:23]
	s_lshl_b32 s10, s101, 18
	s_mov_b32 s11, 0
	v_lshl_add_u64 v[78:79], v[78:79], 0, s[10:11]
	s_mov_b32 s11, 0xea80000
	v_add_co_u32_e64 v80, s[22:23], s11, v78
	s_mov_b32 s11, 0xeaa0000
	s_nop 1
	v_addc_co_u32_e64 v81, s[22:23], 0, v79, s[22:23]
	v_add_co_u32_e64 v82, s[22:23], s11, v78
	s_nop 1
	v_addc_co_u32_e64 v83, s[22:23], 0, v79, s[22:23]
	global_load_dwordx4 v[118:121], v[76:77], off
	global_load_dwordx4 v[122:125], v[76:77], off offset:64
	global_load_dwordx4 v[126:129], v[80:81], off
	global_load_dwordx4 v[130:133], v[80:81], off offset:64
	global_load_dwordx4 v[134:137], v[82:83], off
	global_load_dwordx4 v[138:141], v[82:83], off offset:64
	global_load_dwordx4 v[142:145], v[76:77], off offset:128
	global_load_dwordx4 v[146:149], v[76:77], off offset:192
	global_load_dwordx4 v[150:153], v[80:81], off offset:128
	global_load_dwordx4 v[154:157], v[80:81], off offset:192
	global_load_dwordx4 v[158:161], v[82:83], off offset:128
	global_load_dwordx4 v[162:165], v[82:83], off offset:192
	global_load_dwordx4 v[166:169], v[76:77], off offset:256
	global_load_dwordx4 v[182:185], v[76:77], off offset:320
	global_load_dwordx4 v[186:189], v[80:81], off offset:256
	global_load_dwordx4 v[190:193], v[80:81], off offset:320
	global_load_dwordx4 v[194:197], v[82:83], off offset:256
	global_load_dwordx4 v[202:205], v[82:83], off offset:320
	global_load_dwordx4 v[206:209], v[76:77], off offset:384
	global_load_dwordx4 v[210:213], v[76:77], off offset:448
	global_load_dwordx4 v[214:217], v[80:81], off offset:384
	global_load_dwordx4 v[220:223], v[80:81], off offset:448
	global_load_dwordx4 v[224:227], v[82:83], off offset:384
	global_load_dwordx4 v[228:231], v[82:83], off offset:448
	s_waitcnt vmcnt(22)
	ds_bpermute_b32 v118, v248, v118
	ds_bpermute_b32 v119, v248, v119
	ds_bpermute_b32 v120, v248, v120
	ds_bpermute_b32 v121, v248, v121
	ds_bpermute_b32 v122, v248, v122
	ds_bpermute_b32 v123, v248, v123
	ds_bpermute_b32 v124, v248, v124
	ds_bpermute_b32 v125, v248, v125
	s_waitcnt vmcnt(20) lgkmcnt(7)
	ds_bpermute_b32 v126, v248, v126
	ds_bpermute_b32 v127, v248, v127
	ds_bpermute_b32 v128, v248, v128
	ds_bpermute_b32 v129, v248, v129
	ds_bpermute_b32 v130, v248, v130
	ds_bpermute_b32 v131, v248, v131
	ds_bpermute_b32 v132, v248, v132
	ds_bpermute_b32 v133, v248, v133
	s_waitcnt lgkmcnt(8)
	s_waitcnt vmcnt(18) lgkmcnt(7)
	ds_bpermute_b32 v134, v248, v134
	ds_bpermute_b32 v135, v248, v135
	ds_bpermute_b32 v136, v248, v136
	ds_bpermute_b32 v137, v248, v137
	ds_bpermute_b32 v138, v248, v138
	ds_bpermute_b32 v139, v248, v139
	ds_bpermute_b32 v140, v248, v140
	ds_bpermute_b32 v141, v248, v141
	s_waitcnt lgkmcnt(8)
	s_waitcnt vmcnt(16) lgkmcnt(7)
	ds_bpermute_b32 v142, v248, v142
	ds_bpermute_b32 v143, v248, v143
	ds_bpermute_b32 v144, v248, v144
	ds_bpermute_b32 v145, v248, v145
	ds_bpermute_b32 v146, v248, v146
	ds_bpermute_b32 v147, v248, v147
	ds_bpermute_b32 v148, v248, v148
	ds_bpermute_b32 v149, v248, v149
	s_waitcnt lgkmcnt(8)
	v_mfma_f32_16x16x32_bf16 v[28:31], v[118:121], v[126:129], v[28:31]
	v_mfma_f32_16x16x32_bf16 v[24:27], v[118:121], v[134:137], v[24:27]
	v_mfma_f32_16x16x32_bf16 v[28:31], v[122:125], v[130:133], v[28:31]
	v_mfma_f32_16x16x32_bf16 v[24:27], v[122:125], v[138:141], v[24:27]
	global_load_dwordx4 v[118:121], v[76:77], off offset:512
	global_load_dwordx4 v[122:125], v[76:77], off offset:576
	global_load_dwordx4 v[126:129], v[80:81], off offset:512
	global_load_dwordx4 v[130:133], v[80:81], off offset:576
	global_load_dwordx4 v[134:137], v[82:83], off offset:512
	global_load_dwordx4 v[138:141], v[82:83], off offset:576
	s_waitcnt vmcnt(20) lgkmcnt(7)
	ds_bpermute_b32 v150, v248, v150
	ds_bpermute_b32 v151, v248, v151
	ds_bpermute_b32 v152, v248, v152
	ds_bpermute_b32 v153, v248, v153
	ds_bpermute_b32 v154, v248, v154
	ds_bpermute_b32 v155, v248, v155
	ds_bpermute_b32 v156, v248, v156
	ds_bpermute_b32 v157, v248, v157
	s_waitcnt lgkmcnt(8)
	s_waitcnt vmcnt(18) lgkmcnt(7)
	ds_bpermute_b32 v158, v248, v158
	ds_bpermute_b32 v159, v248, v159
	ds_bpermute_b32 v160, v248, v160
	ds_bpermute_b32 v161, v248, v161
	ds_bpermute_b32 v162, v248, v162
	ds_bpermute_b32 v163, v248, v163
	ds_bpermute_b32 v164, v248, v164
	ds_bpermute_b32 v165, v248, v165
	s_waitcnt lgkmcnt(8)
	s_waitcnt vmcnt(16) lgkmcnt(7)
	ds_bpermute_b32 v166, v248, v166
	ds_bpermute_b32 v167, v248, v167
	ds_bpermute_b32 v168, v248, v168
	ds_bpermute_b32 v169, v248, v169
	ds_bpermute_b32 v182, v248, v182
	ds_bpermute_b32 v183, v248, v183
	ds_bpermute_b32 v184, v248, v184
	ds_bpermute_b32 v185, v248, v185
	s_waitcnt lgkmcnt(8)
	v_mfma_f32_16x16x32_bf16 v[28:31], v[142:145], v[150:153], v[28:31]
	v_mfma_f32_16x16x32_bf16 v[24:27], v[142:145], v[158:161], v[24:27]
	v_mfma_f32_16x16x32_bf16 v[28:31], v[146:149], v[154:157], v[28:31]
	v_mfma_f32_16x16x32_bf16 v[24:27], v[146:149], v[162:165], v[24:27]
	global_load_dwordx4 v[142:145], v[76:77], off offset:640
	global_load_dwordx4 v[146:149], v[76:77], off offset:704
	global_load_dwordx4 v[150:153], v[80:81], off offset:640
	global_load_dwordx4 v[154:157], v[80:81], off offset:704
	global_load_dwordx4 v[158:161], v[82:83], off offset:640
	global_load_dwordx4 v[162:165], v[82:83], off offset:704
	s_waitcnt vmcnt(20) lgkmcnt(7)
	ds_bpermute_b32 v186, v248, v186
	ds_bpermute_b32 v187, v248, v187
	ds_bpermute_b32 v188, v248, v188
	ds_bpermute_b32 v189, v248, v189
	ds_bpermute_b32 v190, v248, v190
	ds_bpermute_b32 v191, v248, v191
	ds_bpermute_b32 v192, v248, v192
	ds_bpermute_b32 v193, v248, v193
	s_waitcnt lgkmcnt(8)
	s_waitcnt vmcnt(18) lgkmcnt(7)
	ds_bpermute_b32 v194, v248, v194
	ds_bpermute_b32 v195, v248, v195
	ds_bpermute_b32 v196, v248, v196
	ds_bpermute_b32 v197, v248, v197
	ds_bpermute_b32 v202, v248, v202
	ds_bpermute_b32 v203, v248, v203
	ds_bpermute_b32 v204, v248, v204
	ds_bpermute_b32 v205, v248, v205
	s_waitcnt lgkmcnt(8)
	s_waitcnt vmcnt(16) lgkmcnt(7)
	ds_bpermute_b32 v206, v248, v206
	ds_bpermute_b32 v207, v248, v207
	ds_bpermute_b32 v208, v248, v208
	ds_bpermute_b32 v209, v248, v209
	ds_bpermute_b32 v210, v248, v210
	ds_bpermute_b32 v211, v248, v211
	ds_bpermute_b32 v212, v248, v212
	ds_bpermute_b32 v213, v248, v213
	s_waitcnt lgkmcnt(8)
	v_mfma_f32_16x16x32_bf16 v[28:31], v[166:169], v[186:189], v[28:31]
	v_mfma_f32_16x16x32_bf16 v[24:27], v[166:169], v[194:197], v[24:27]
	v_mfma_f32_16x16x32_bf16 v[28:31], v[182:185], v[190:193], v[28:31]
	v_mfma_f32_16x16x32_bf16 v[24:27], v[182:185], v[202:205], v[24:27]
	global_load_dwordx4 v[166:169], v[76:77], off offset:768
	global_load_dwordx4 v[182:185], v[76:77], off offset:832
	global_load_dwordx4 v[186:189], v[80:81], off offset:768
	global_load_dwordx4 v[190:193], v[80:81], off offset:832
	global_load_dwordx4 v[194:197], v[82:83], off offset:768
	global_load_dwordx4 v[202:205], v[82:83], off offset:832
	s_waitcnt vmcnt(20) lgkmcnt(7)
	ds_bpermute_b32 v214, v248, v214
	ds_bpermute_b32 v215, v248, v215
	ds_bpermute_b32 v216, v248, v216
	ds_bpermute_b32 v217, v248, v217
	ds_bpermute_b32 v220, v248, v220
	ds_bpermute_b32 v221, v248, v221
	ds_bpermute_b32 v222, v248, v222
	ds_bpermute_b32 v223, v248, v223
	s_waitcnt lgkmcnt(8)
	s_waitcnt vmcnt(18) lgkmcnt(7)
	ds_bpermute_b32 v224, v248, v224
	ds_bpermute_b32 v225, v248, v225
	ds_bpermute_b32 v226, v248, v226
	ds_bpermute_b32 v227, v248, v227
	ds_bpermute_b32 v228, v248, v228
	ds_bpermute_b32 v229, v248, v229
	ds_bpermute_b32 v230, v248, v230
	ds_bpermute_b32 v231, v248, v231
	s_waitcnt lgkmcnt(8)
	s_waitcnt vmcnt(16) lgkmcnt(7)
	ds_bpermute_b32 v118, v248, v118
	ds_bpermute_b32 v119, v248, v119
	ds_bpermute_b32 v120, v248, v120
	ds_bpermute_b32 v121, v248, v121
	ds_bpermute_b32 v122, v248, v122
	ds_bpermute_b32 v123, v248, v123
	ds_bpermute_b32 v124, v248, v124
	ds_bpermute_b32 v125, v248, v125
	s_waitcnt lgkmcnt(8)
	v_mfma_f32_16x16x32_bf16 v[28:31], v[206:209], v[214:217], v[28:31]
	v_mfma_f32_16x16x32_bf16 v[24:27], v[206:209], v[224:227], v[24:27]
	v_mfma_f32_16x16x32_bf16 v[28:31], v[210:213], v[220:223], v[28:31]
	v_mfma_f32_16x16x32_bf16 v[24:27], v[210:213], v[228:231], v[24:27]
	global_load_dwordx4 v[206:209], v[76:77], off offset:896
	global_load_dwordx4 v[210:213], v[76:77], off offset:960
	global_load_dwordx4 v[214:217], v[80:81], off offset:896
	global_load_dwordx4 v[220:223], v[80:81], off offset:960
	global_load_dwordx4 v[224:227], v[82:83], off offset:896
	global_load_dwordx4 v[228:231], v[82:83], off offset:960
	s_waitcnt vmcnt(20) lgkmcnt(7)
	ds_bpermute_b32 v126, v248, v126
	ds_bpermute_b32 v127, v248, v127
	ds_bpermute_b32 v128, v248, v128
	ds_bpermute_b32 v129, v248, v129
	ds_bpermute_b32 v130, v248, v130
	ds_bpermute_b32 v131, v248, v131
	ds_bpermute_b32 v132, v248, v132
	ds_bpermute_b32 v133, v248, v133
	s_waitcnt lgkmcnt(8)
	s_waitcnt vmcnt(18) lgkmcnt(7)
	ds_bpermute_b32 v134, v248, v134
	ds_bpermute_b32 v135, v248, v135
	ds_bpermute_b32 v136, v248, v136
	ds_bpermute_b32 v137, v248, v137
	ds_bpermute_b32 v138, v248, v138
	ds_bpermute_b32 v139, v248, v139
	ds_bpermute_b32 v140, v248, v140
	ds_bpermute_b32 v141, v248, v141
	s_waitcnt lgkmcnt(8)
	s_waitcnt vmcnt(16) lgkmcnt(7)
	ds_bpermute_b32 v142, v248, v142
	ds_bpermute_b32 v143, v248, v143
	ds_bpermute_b32 v144, v248, v144
	ds_bpermute_b32 v145, v248, v145
	ds_bpermute_b32 v146, v248, v146
	ds_bpermute_b32 v147, v248, v147
	ds_bpermute_b32 v148, v248, v148
	ds_bpermute_b32 v149, v248, v149
	s_waitcnt lgkmcnt(8)
	v_mfma_f32_16x16x32_bf16 v[28:31], v[118:121], v[126:129], v[28:31]
	v_mfma_f32_16x16x32_bf16 v[24:27], v[118:121], v[134:137], v[24:27]
	v_mfma_f32_16x16x32_bf16 v[28:31], v[122:125], v[130:133], v[28:31]
	v_mfma_f32_16x16x32_bf16 v[24:27], v[122:125], v[138:141], v[24:27]
	s_waitcnt vmcnt(14) lgkmcnt(7)
	ds_bpermute_b32 v150, v248, v150
	ds_bpermute_b32 v151, v248, v151
	ds_bpermute_b32 v152, v248, v152
	ds_bpermute_b32 v153, v248, v153
	ds_bpermute_b32 v154, v248, v154
	ds_bpermute_b32 v155, v248, v155
	ds_bpermute_b32 v156, v248, v156
	ds_bpermute_b32 v157, v248, v157
	s_waitcnt lgkmcnt(8)
	s_waitcnt vmcnt(12) lgkmcnt(7)
	ds_bpermute_b32 v158, v248, v158
	ds_bpermute_b32 v159, v248, v159
	ds_bpermute_b32 v160, v248, v160
	ds_bpermute_b32 v161, v248, v161
	ds_bpermute_b32 v162, v248, v162
	ds_bpermute_b32 v163, v248, v163
	ds_bpermute_b32 v164, v248, v164
	ds_bpermute_b32 v165, v248, v165
	s_waitcnt lgkmcnt(8)
	s_waitcnt vmcnt(10) lgkmcnt(7)
	ds_bpermute_b32 v166, v248, v166
	ds_bpermute_b32 v167, v248, v167
	ds_bpermute_b32 v168, v248, v168
	ds_bpermute_b32 v169, v248, v169
	ds_bpermute_b32 v182, v248, v182
	ds_bpermute_b32 v183, v248, v183
	ds_bpermute_b32 v184, v248, v184
	ds_bpermute_b32 v185, v248, v185
	s_waitcnt lgkmcnt(8)
	v_mfma_f32_16x16x32_bf16 v[28:31], v[142:145], v[150:153], v[28:31]
	v_mfma_f32_16x16x32_bf16 v[24:27], v[142:145], v[158:161], v[24:27]
	v_mfma_f32_16x16x32_bf16 v[28:31], v[146:149], v[154:157], v[28:31]
	v_mfma_f32_16x16x32_bf16 v[24:27], v[146:149], v[162:165], v[24:27]
	s_waitcnt vmcnt(8) lgkmcnt(7)
	ds_bpermute_b32 v186, v248, v186
	ds_bpermute_b32 v187, v248, v187
	ds_bpermute_b32 v188, v248, v188
	ds_bpermute_b32 v189, v248, v189
	ds_bpermute_b32 v190, v248, v190
	ds_bpermute_b32 v191, v248, v191
	ds_bpermute_b32 v192, v248, v192
	ds_bpermute_b32 v193, v248, v193
	s_waitcnt lgkmcnt(8)
	s_waitcnt vmcnt(6) lgkmcnt(7)
	ds_bpermute_b32 v194, v248, v194
	ds_bpermute_b32 v195, v248, v195
	ds_bpermute_b32 v196, v248, v196
	ds_bpermute_b32 v197, v248, v197
	ds_bpermute_b32 v202, v248, v202
	ds_bpermute_b32 v203, v248, v203
	ds_bpermute_b32 v204, v248, v204
	ds_bpermute_b32 v205, v248, v205
	s_waitcnt lgkmcnt(8)
	s_waitcnt vmcnt(4) lgkmcnt(7)
	ds_bpermute_b32 v206, v248, v206
	ds_bpermute_b32 v207, v248, v207
	ds_bpermute_b32 v208, v248, v208
	ds_bpermute_b32 v209, v248, v209
	ds_bpermute_b32 v210, v248, v210
	ds_bpermute_b32 v211, v248, v211
	ds_bpermute_b32 v212, v248, v212
	ds_bpermute_b32 v213, v248, v213
	s_waitcnt lgkmcnt(8)
	v_mfma_f32_16x16x32_bf16 v[28:31], v[166:169], v[186:189], v[28:31]
	v_mfma_f32_16x16x32_bf16 v[24:27], v[166:169], v[194:197], v[24:27]
	v_mfma_f32_16x16x32_bf16 v[28:31], v[182:185], v[190:193], v[28:31]
	v_mfma_f32_16x16x32_bf16 v[24:27], v[182:185], v[202:205], v[24:27]
	s_waitcnt vmcnt(2) lgkmcnt(7)
	ds_bpermute_b32 v214, v248, v214
	ds_bpermute_b32 v215, v248, v215
	ds_bpermute_b32 v216, v248, v216
	ds_bpermute_b32 v217, v248, v217
	ds_bpermute_b32 v220, v248, v220
	ds_bpermute_b32 v221, v248, v221
	ds_bpermute_b32 v222, v248, v222
	ds_bpermute_b32 v223, v248, v223
	s_waitcnt lgkmcnt(8)
	s_waitcnt vmcnt(0) lgkmcnt(7)
	ds_bpermute_b32 v224, v248, v224
	ds_bpermute_b32 v225, v248, v225
	ds_bpermute_b32 v226, v248, v226
	ds_bpermute_b32 v227, v248, v227
	ds_bpermute_b32 v228, v248, v228
	ds_bpermute_b32 v229, v248, v229
	ds_bpermute_b32 v230, v248, v230
	ds_bpermute_b32 v231, v248, v231
	s_waitcnt lgkmcnt(8)
	s_waitcnt lgkmcnt(0)
	v_mfma_f32_16x16x32_bf16 v[28:31], v[206:209], v[214:217], v[28:31]
	v_mfma_f32_16x16x32_bf16 v[24:27], v[206:209], v[224:227], v[24:27]
	v_mfma_f32_16x16x32_bf16 v[28:31], v[210:213], v[220:223], v[28:31]
	v_mfma_f32_16x16x32_bf16 v[24:27], v[210:213], v[228:231], v[24:27]
	s_nop 4
	s_waitcnt lgkmcnt(0)
	v_pk_add_f32 v[52:53], v[54:55], v[56:57]
	s_nop 0
	v_pk_mul_f32 v[52:53], v[52:53], s[6:7] op_sel_hi:[1,0]
	s_nop 0
	v_fma_f32 v49, -v52, v52, v53
	v_max_f32_e32 v49, 0, v49
	v_add_f32_e32 v49, 0x3727c5ac, v49
	v_mul_f32_e32 v53, 0x4b800000, v49
	v_cmp_gt_f32_e64 s[22:23], s14, v49
	s_nop 1
	v_cndmask_b32_e64 v49, v49, v53, s[22:23]
	v_rsq_f32_e32 v49, v49
	v_add_u32_e32 v53, s4, v64
	v_lshl_add_u32 v53, s101, 11, v53
	ds_write_b128 v53, v[28:31]
	ds_write_b128 v53, v[24:27] offset:1024
	v_add_u32_e32 v23, s12, v64
	s_waitcnt lgkmcnt(0)
	s_barrier
	s_lshr_b32 s10, s12, 11
	s_cmp_lg_u32 s10, s101
	s_cbranch_scc1 .LBB0_1373
	ds_read_b128 v[8:11], v23
	ds_read_b128 v[12:15], v23 offset:8192
	v_mul_f32_e32 v16, 0x45800000, v49
	v_cndmask_b32_e64 v22, v49, v16, s[22:23]
	ds_read_b128 v[16:19], v23 offset:16384
	s_waitcnt lgkmcnt(2)
	v_pk_add_f32 v[10:11], v[10:11], 0 op_sel_hi:[1,0]
	v_pk_add_f32 v[20:21], v[8:9], 0 op_sel_hi:[1,0]
	s_waitcnt lgkmcnt(1)
	v_pk_add_f32 v[14:15], v[10:11], v[14:15]
	ds_read_b128 v[8:11], v23 offset:24576
	v_pk_add_f32 v[20:21], v[20:21], v[12:13]
	s_waitcnt lgkmcnt(1)
	v_pk_add_f32 v[18:19], v[14:15], v[18:19]
	ds_read_b128 v[12:15], v23 offset:32768
	v_pk_add_f32 v[16:17], v[20:21], v[16:17]
	s_waitcnt lgkmcnt(1)
	v_pk_add_f32 v[18:19], v[18:19], v[10:11]
	v_pk_add_f32 v[20:21], v[16:17], v[8:9]
	ds_read_b128 v[8:11], v23 offset:40960
	s_waitcnt lgkmcnt(1)
	v_pk_add_f32 v[24:25], v[18:19], v[14:15]
	ds_read_b128 v[14:17], v23 offset:49152
	v_pk_add_f32 v[12:13], v[20:21], v[12:13]
	ds_read_b128 v[18:21], v23 offset:57344
	s_waitcnt lgkmcnt(2)
	v_pk_add_f32 v[8:9], v[12:13], v[8:9]
	v_lshlrev_b32_e32 v12, 16, v60
	s_waitcnt lgkmcnt(1)
	v_pk_add_f32 v[8:9], v[8:9], v[14:15]
	v_and_b32_e32 v13, 0xffff0000, v60
	v_lshlrev_b32_e32 v14, 16, v61
	v_and_b32_e32 v15, 0xffff0000, v61
	v_pk_add_f32 v[10:11], v[24:25], v[10:11]
	v_sub_f32_e32 v13, v13, v52
	v_sub_f32_e32 v12, v12, v52
	v_sub_f32_e32 v15, v15, v52
	v_sub_f32_e32 v14, v14, v52
	v_pk_add_f32 v[10:11], v[10:11], v[16:17]
	v_pk_mul_f32 v[14:15], v[14:15], v[22:23] op_sel_hi:[1,0]
	v_pk_mul_f32 v[12:13], v[12:13], v[22:23] op_sel_hi:[1,0]
	s_waitcnt lgkmcnt(0)
	v_pk_add_f32 v[10:11], v[10:11], v[20:21]
	v_pk_add_f32 v[8:9], v[8:9], v[18:19]
	v_pk_fma_f32 v[0:1], v[0:1], v[12:13], v[4:5]
	v_pk_fma_f32 v[2:3], v[2:3], v[14:15], v[6:7]
	v_pk_fma_f32 v[6:7], v[0:1], s[70:71], v[8:9] op_sel_hi:[1,0,1]
	v_pk_fma_f32 v[4:5], v[2:3], s[70:71], v[10:11] op_sel_hi:[1,0,1]
	v_mul_f32_e32 v1, v6, v6
	v_mul_f32_e32 v3, v7, v7
	v_mul_f32_e32 v9, v4, v4
	v_mul_f32_e32 v11, v5, v5
	v_mov_b32_e32 v0, v6
	v_mov_b32_e32 v2, v7
	v_mov_b32_e32 v8, v4
	v_mov_b32_e32 v10, v5
	v_pk_add_f32 v[0:1], v[0:1], v[2:3]
	v_pk_add_f32 v[2:3], v[8:9], v[10:11]
	v_cvt_pk_bf16_f32 v6, v6, v7
	v_cvt_pk_bf16_f32 v7, v4, v5
	global_store_dwordx2 v[58:59], v[6:7], off
	v_pk_add_f32 v[0:1], v[0:1], v[2:3]
	ds_bpermute_b32 v2, v66, v0
	ds_bpermute_b32 v3, v66, v1
	s_waitcnt lgkmcnt(0)
	v_pk_add_f32 v[0:1], v[0:1], v[2:3]
	ds_bpermute_b32 v2, v67, v0
	ds_bpermute_b32 v3, v67, v1
	s_and_saveexec_b64 s[10:11], vcc
	s_cbranch_execz .LBB0_1373
	s_lshl_b32 s16, s100, 1
	s_ashr_i32 s17, s16, 31
	v_lshl_add_u64 v[4:5], s[16:17], 2, v[44:45]
	s_waitcnt lgkmcnt(0)
	v_pk_add_f32 v[0:1], v[0:1], v[2:3]
	global_store_dwordx2 v[4:5], v[0:1], off
	s_branch .LBB0_1373
